# pop order GEMV|S5|pool weights|norm items|weight copies with write-through copy stores (no dirty weights at the P0 barrier), on top of v66
# baseline (speedup 1.0000x reference)
.LBB0_39:
	s_or_b64 exec, exec, s[8:9]
	s_xor_b64 s[8:9], s[48:49], -1
	s_andn2_b64 vcc, exec, s[6:7]
	s_mov_b64 s[52:53], -1
	s_barrier
	s_cbranch_vccnz .LBB0_32
	s_add_i32 s6, s36, 0xc0
	s_add_i32 s7, s36, 0xffffff00
	s_cmpk_lt_i32 s36, 0x100
	s_cselect_b32 s44, s6, s7
	s_cmpk_lt_i32 s36, 0x1c0
	s_cbranch_scc1 .Lpop_map_done
	s_add_i32 s44, s36, s70
	s_cmpk_lt_i32 s36, 0x3d0
	s_cbranch_scc1 .Lpop_map_done
	s_add_i32 s44, s36, 0xfffffdf0
.Lpop_map_done:
	v_and_b32_e32 v80, 63, v79
	s_cmpk_gt_i32 s44, 0x7f
	s_cbranch_scc0 .LBB0_103
	s_cmpk_gt_u32 s44, 0xbf
	s_cbranch_scc0 .LBB0_98
	s_cmpk_gt_u32 s44, 0x1bf
	s_cbranch_scc0 .LBB0_75
	s_add_i32 s45, s44, 0xfffffe40
	s_mov_b64 s[6:7], -1
	s_cmp_ge_i32 s45, s70
	s_cbranch_scc0 .LBB0_65
	s_andn2_b64 vcc, exec, s[8:9]
	s_cbranch_vccnz .LBB0_56
	s_and_saveexec_b64 s[8:9], s[4:5]
	s_cbranch_execz .LBB0_55
	s_mov_b32 s36, 0x400001
	s_branch .LBB0_48

.LBB0_269:
	s_mov_b32 s59, s37
	s_lshl_b64 s[54:55], s[58:59], 1
	s_add_u32 s52, s52, s54
	s_addc_u32 s53, s53, s55
	v_lshlrev_b32_e32 v66, 1, v2
	s_waitcnt lgkmcnt(3)
	v_perm_b32 v16, v5, v4, s89
	s_waitcnt lgkmcnt(2)
	v_perm_b32 v17, v7, v6, s89
	s_waitcnt lgkmcnt(1)
	v_perm_b32 v18, v9, v8, s89
	v_perm_b32 v4, v5, v4, s97
	v_perm_b32 v5, v7, v6, s97
	v_perm_b32 v6, v9, v8, s97
	v_ashrrev_i32_e32 v8, 31, v14
	v_lshl_add_u64 v[2:3], s[52:53], 0, v[66:67]
	s_waitcnt lgkmcnt(0)
	v_perm_b32 v19, v11, v10, s89
	v_perm_b32 v7, v11, v10, s97
	v_mul_lo_u32 v10, s9, v14
	v_mul_lo_u32 v11, s8, v8
	v_mad_u64_u32 v[8:9], s[52:53], s8, v14, 0
	v_add3_u32 v9, v9, v11, v10
	v_lshl_add_u64 v[8:9], v[8:9], 1, v[2:3]
	global_store_dwordx4 v[8:9], v[16:19], off sc1
	v_lshl_add_u64 v[8:9], s[8:9], 1, v[8:9]
	v_ashrrev_i32_e32 v12, 3, v12
	global_store_dwordx4 v[8:9], v[4:7], off sc1
	v_lshlrev_b32_e32 v14, 1, v12
	s_andn2_b64 vcc, exec, s[56:57]
	v_lshlrev_b32_e32 v4, 2, v12
	v_add3_u32 v10, 0, v4, v13
	ds_read2_b32 v[4:5], v10 offset1:129
	v_add_u32_e32 v6, 0x400, v10
	v_add_u32_e32 v8, 0x800, v10
	v_add_u32_e32 v10, 0xc00, v10
	ds_read2_b32 v[6:7], v6 offset0:2 offset1:131
	ds_read2_b32 v[8:9], v8 offset0:4 offset1:133
	ds_read2_b32 v[10:11], v10 offset0:6 offset1:135
	v_add_u32_e32 v12, s36, v14
	s_mov_b64 s[52:53], -1
	s_cbranch_vccnz .LBB0_273
	s_movk_i32 s36, 0x3ff
	v_cmp_lt_i32_e32 vcc, s36, v12
	s_and_b64 s[52:53], s[6:7], vcc
	v_mov_b32_e32 v13, v12
	s_and_saveexec_b64 s[6:7], s[52:53]
	v_add_u32_e32 v13, 0xfffffc00, v12
	v_lshlrev_b32_e32 v15, 1, v12
	v_lshrrev_b32_e32 v13, 3, v13
	v_and_b32_e32 v14, 0x7e, v14
	s_movk_i32 s36, 0x700
	v_and_b32_e32 v13, 0x1fffff80, v13
	v_and_or_b32 v14, v15, s36, v14
	s_movk_i32 s36, 0x400
	v_add3_u32 v13, v14, v13, s36
	s_or_b64 exec, exec, s[6:7]
	s_mov_b64 s[52:53], 0

.LBB0_275:
	s_waitcnt lgkmcnt(3)
	v_perm_b32 v14, v5, v4, s97
	s_waitcnt lgkmcnt(2)
	v_perm_b32 v15, v7, v6, s97
	s_waitcnt lgkmcnt(1)
	v_perm_b32 v16, v9, v8, s97
	v_perm_b32 v4, v5, v4, s89
	v_perm_b32 v5, v7, v6, s89
	v_perm_b32 v6, v9, v8, s89
	v_ashrrev_i32_e32 v8, 31, v13
	s_waitcnt lgkmcnt(0)
	v_perm_b32 v17, v11, v10, s97
	v_perm_b32 v7, v11, v10, s89
	v_mul_lo_u32 v10, s9, v13
	v_mul_lo_u32 v11, s8, v8
	v_mad_u64_u32 v[8:9], s[6:7], s8, v13, 0
	v_add3_u32 v9, v9, v11, v10
	v_lshl_add_u64 v[2:3], v[8:9], 1, v[2:3]
	global_store_dwordx4 v[2:3], v[4:7], off sc1
	v_lshl_add_u64 v[2:3], s[8:9], 1, v[2:3]
	global_store_dwordx4 v[2:3], v[14:17], off sc1
	s_barrier
	s_mov_b64 s[6:7], s[48:49]
	s_cbranch_execz .LBB0_76
	s_branch .LBB0_97
